# mem f32 read-once loads of the prep conversion loop marked nt (same class as the x stream), on top of merge counted wait
# baseline (speedup 1.0000x reference)
; __device__ __forceinline__ unsigned cvt_pk_bf16(float lo, float hi) { const f32x2v v = {lo, hi}; const b16x2v r = __builtin_convertvector(v, b16x2v); return __builtin_bit_cast(unsigned, r); }
; __device__ void prep_phase(const Params& p, unsigned char* smem_g) {
;     ...
;     { bf16_t* mb = (bf16_t*)(ws + OFF_MEMB);
;       for (int e = blockIdx.x * 512 + tid; e < 1024 * 2048 / 4; e += gridDim.x * 512) { const f32x4 v = *(const f32x4*)(p.mem + (size_t)e * 4); u32x2 w; w.x = cvt_pk_bf16(v[0], v[1]); w.y = cvt_pk_bf16(v[2], v[3]); *(u32x2*)(mb + (size_t)e * 4) = w; } }
.LBB0_150:
	v_add_u32_e32 v8, s70, v0
	v_add_u32_e32 v9, s70, v8
	v_add_u32_e32 v10, s70, v9
	v_min_i32_e32 v12, v8, v11
	v_min_i32_e32 v13, v9, v11
	v_min_i32_e32 v14, v10, v11
	v_lshlrev_b32_e32 v28, 4, v0
	v_lshlrev_b32_e32 v29, 4, v12
	v_lshlrev_b32_e32 v30, 4, v13
	v_lshlrev_b32_e32 v31, 4, v14
	global_load_dwordx4 v[4:7], v28, s[74:75] nt
	global_load_dwordx4 v[16:19], v29, s[74:75] nt
	global_load_dwordx4 v[20:23], v30, s[74:75] nt
	global_load_dwordx4 v[24:27], v31, s[74:75] nt
	v_lshlrev_b32_e32 v28, 3, v0
	v_lshlrev_b32_e32 v29, 3, v8
	v_lshlrev_b32_e32 v30, 3, v9
	v_lshlrev_b32_e32 v31, 3, v10
	s_mov_b64 s[8:9], exec
	s_waitcnt vmcnt(3)
	v_cvt_pk_bf16_f32 v4, v4, v5
	v_cvt_pk_bf16_f32 v5, v6, v7
	global_store_dwordx2 v28, v[4:5], s[6:7]
	s_waitcnt vmcnt(0)
	v_cvt_pk_bf16_f32 v16, v16, v17
	v_cvt_pk_bf16_f32 v17, v18, v19
	v_cvt_pk_bf16_f32 v20, v20, v21
	v_cvt_pk_bf16_f32 v21, v22, v23
	v_cvt_pk_bf16_f32 v24, v24, v25
	v_cvt_pk_bf16_f32 v25, v26, v27
	v_cmp_gt_i32_e32 vcc, s4, v8
	s_and_b64 exec, exec, vcc
	global_store_dwordx2 v29, v[16:17], s[6:7]
	v_cmp_gt_i32_e32 vcc, s4, v9
	s_and_b64 exec, exec, vcc
	global_store_dwordx2 v30, v[20:21], s[6:7]
	v_cmp_gt_i32_e32 vcc, s4, v10
	s_and_b64 exec, exec, vcc
	global_store_dwordx2 v31, v[24:25], s[6:7]
	s_mov_b64 exec, s[8:9]
	v_add_u32_e32 v0, s70, v10
	v_cmp_le_i32_e32 vcc, s4, v0
	s_or_b64 s[2:3], vcc, s[2:3]
	s_andn2_b64 exec, exec, s[2:3]
	s_cbranch_execnz .LBB0_150
